# attention key loop: wave-uniform exit test reads the flag mask SGPR pair directly (s_cmp_eq_u64) instead of a cndmask/v_cmp/ballot round trip
# speedup vs baseline: 1.0129x; 1.0023x over previous
;     ...
;         if (it + 1 < NT) { kreg = *(const u32x4*)(kg + (size_t)(kt - 1) * 64 * 1024); vreg = *(const u32x4*)(vg + (size_t)(kt - 1) * 64 * 1024); }
;     ...
;         if (lane == 0) aflag[(it & 1) * 8 + wid] = (unsigned)alive;
;         __syncthreads();
;         const unsigned fl = (lane < 8) ? aflag[(it & 1) * 8 + lane] : 0u;
;         if (!__any(fl != 0u)) break;
.LBB0_469:
	s_or_b64 exec, exec, s[4:5]
	s_cmp_eq_u64 s[6:7], 0
	s_cselect_b64 s[4:5], -1, 0
	v_lshl_add_u64 v[90:91], v[90:91], 0, s[16:17]
	v_lshl_add_u64 v[92:93], v[92:93], 0, s[16:17]
	s_sub_i32 s27, s27, 64
	s_and_b64 vcc, exec, s[4:5]
	s_cbranch_vccnz .LBB0_456
